# split-phase rendezvous: barriers after down1 and after W_out stay XCD-local, XCD leaders arrive on global counters, the overlay-writing code of the next phase checks the counter first
# speedup vs baseline: 1.0094x; 1.0094x over previous
; __device__ __forceinline__ unsigned xb_add(unsigned* p, unsigned v) { return __hip_atomic_fetch_add(p, v, __ATOMIC_RELAXED, __HIP_MEMORY_SCOPE_AGENT); }
; __device__ __forceinline__ void xcd_barrier(const XcdBarrier& b) {
;     asm volatile("s_waitcnt vmcnt(0)" ::: "memory");
;     __syncthreads();
;     if (threadIdx.x == 0) {
;         unsigned* bar = b.bar;
;         __builtin_amdgcn_s_waitcnt(0);
;         unsigned nloc = b.st[0], nx = b.st[1];
;         if (nloc == 0u) { xcd_barrier_complete(bar, b.x, nloc, nx); b.st[0] = nloc; b.st[1] = nx; }
;         const unsigned old = xb_add(&bar[XB_XSUB(b.x)], 1u);
.LBB0_899:
	s_waitcnt vmcnt(0)
	s_waitcnt lgkmcnt(0)
	s_barrier
	s_mov_b64 s[2:3], exec
	v_readlane_b32 s6, v252, 10
	v_readlane_b32 s7, v252, 11
	s_and_b64 s[6:7], s[2:3], s[6:7]
	s_mov_b64 exec, s[6:7]
	s_cbranch_execz .LBB0_951
	v_mov_b32_e32 v4, 0x26a24
	ds_read_b32 v5, v4
	ds_read_b32 v6, v4 offset:28
	s_waitcnt lgkmcnt(0)
	v_add_u32_e32 v5, v6, v5
	ds_write_b32 v4, v5 offset:28
	v_readlane_b32 s1, v255, 21
	s_waitcnt vmcnt(0) expcnt(0) lgkmcnt(0)
	s_nop 0
	v_mov_b32_e32 v1, s1
	ds_read_b32 v3, v1
	v_readlane_b32 s1, v255, 22
	s_waitcnt lgkmcnt(0)
	v_cmp_ne_u32_e32 vcc, 0, v3
	v_mov_b32_e32 v1, s1
	ds_read_b32 v2, v1
	s_cbranch_vccnz .LBB0_915
	s_mov_b32 s4, 1
	s_branch .LBB0_903

; __device__ __forceinline__ unsigned xb_add(unsigned* p, unsigned v) { return __hip_atomic_fetch_add(p, v, __ATOMIC_RELAXED, __HIP_MEMORY_SCOPE_AGENT); }
; __device__ __forceinline__ void xcd_barrier(const XcdBarrier& b) {
;     ...
;         const unsigned old = xb_add(&bar[XB_XSUB(b.x)], 1u);
;         const unsigned gen = old / nloc;
;         if (old + 1u == (gen + 1u) * nloc) {
;             __builtin_amdgcn_fence(__ATOMIC_RELEASE, "agent");
;             asm volatile("s_waitcnt vmcnt(0)" ::: "memory");
;             const unsigned og = xb_add(&bar[XB_TOP], 1u);
.LBB0_931:
	s_andn2_saveexec_b64 s[6:7], s[6:7]
	s_cbranch_execz .LBB0_951
	v_readlane_b32 s8, v253, 40
	v_readlane_b32 s9, v253, 41
	v_mov_b32_e32 v1, 0x26a38
	ds_read_b32 v1, v1
	s_nop 2
	global_atomic_add v99, v195, s[8:9] offset:512
	s_waitcnt lgkmcnt(0)
	v_cmp_ne_u32_e32 vcc, 0, v1
	s_cbranch_vccnz .Lxcd_local_1
	s_mov_b64 s[6:7], exec
	buffer_wbl2 sc1
	s_waitcnt lgkmcnt(0)
	s_waitcnt vmcnt(0)
	v_mbcnt_lo_u32_b32 v1, s6, 0
	v_mbcnt_hi_u32_b32 v1, s7, v1
	v_cmp_eq_u32_e32 vcc, 0, v1
	s_and_saveexec_b64 s[8:9], vcc
	s_cbranch_execz .LBB0_934
	s_bcnt1_i32_b64 s4, s[6:7]
	v_readlane_b32 s6, v253, 38
	v_mov_b32_e32 v3, s4
	v_readlane_b32 s7, v253, 39
	s_nop 4
	global_atomic_add v3, v99, v3, s[6:7] sc0

; __device__ __forceinline__ float ssf(const ssq_t* p) { return (float)(*p) * (1.0f / 1048576.0f); }
;     __device__ __forceinline__ void operator()(const f32x4 (&acc)[2][2][4][2], const pg8::Unit& u, int wr, int wc, int fr, int fq) const {
;         const int pn = u.pn;
;         const int b = (u.pm * 256) >> 13, tb = ((u.pm * 256) & (S - 1)) + wr * 64 + fr;
;         const int cb = wc * 32 + fq * 8;
;         float rr[2][4];
; #pragma unroll
;         for (int ai = 0; ai < 2; ++ai)
; #pragma unroll
;             for (int m = 0; m < 4; ++m) rr[ai][m] = rsqrtf(ssf(SSin + b * S + tb + ai * 128 + m * 16) * (1.0f / D) + EPS);
;         if (pn < 4) {
;             const float sc = pn < 2 ? QS_SB : 1.0f;
;             bf16* base = (pn < 2 ? SBQ_ : SBK_) + ((size_t)(b * 8 + (pn & 1) * 4 + (cb >> 6)) * S + tb) * 64 + (cb & 63);
.LBB0_970:
	v_mov_b32_e32 v134, 0x26a40
	ds_read_b32 v134, v134
	v_readlane_b32 s16, v253, 40
	v_readlane_b32 s17, v253, 41
	v_mov_b32_e32 v135, 0
	s_mov_b32 s60, 0
	s_waitcnt lgkmcnt(0)
	v_readfirstlane_b32 s4, v134
	s_nop 0
.Lp2done_spin:
	global_load_dword v134, v135, s[16:17] offset:512 sc1
	s_waitcnt vmcnt(0)
	v_readfirstlane_b32 s62, v134
	s_cmp_ge_u32 s62, s4
	s_cbranch_scc1 .Lp2done_ok
	s_sleep 2
	s_add_i32 s60, s60, 1
	s_cmp_lt_u32 s60, 0x100000
	s_cbranch_scc1 .Lp2done_spin

; __device__ __forceinline__ unsigned xb_add(unsigned* p, unsigned v) { return __hip_atomic_fetch_add(p, v, __ATOMIC_RELAXED, __HIP_MEMORY_SCOPE_AGENT); }
; __device__ __forceinline__ void xcd_barrier(const XcdBarrier& b) {
;     asm volatile("s_waitcnt vmcnt(0)" ::: "memory");
;     __syncthreads();
;     if (threadIdx.x == 0) {
;         unsigned* bar = b.bar;
;         __builtin_amdgcn_s_waitcnt(0);
;         unsigned nloc = b.st[0], nx = b.st[1];
;         if (nloc == 0u) { xcd_barrier_complete(bar, b.x, nloc, nx); b.st[0] = nloc; b.st[1] = nx; }
;         const unsigned old = xb_add(&bar[XB_XSUB(b.x)], 1u);
.LBB0_1417:
	s_waitcnt vmcnt(0)
	s_waitcnt lgkmcnt(0)
	s_barrier
	s_mov_b64 s[2:3], exec
	v_readlane_b32 s6, v252, 10
	v_readlane_b32 s7, v252, 11
	s_and_b64 s[6:7], s[2:3], s[6:7]
	v_readlane_b32 s80, v255, 36
	v_readlane_b32 s81, v255, 37
	s_mov_b64 exec, s[6:7]
	s_cbranch_execz .LBB0_1469
	v_mov_b32_e32 v4, 0x26a24
	ds_read_b32 v5, v4
	ds_read_b32 v6, v4 offset:32
	s_waitcnt lgkmcnt(0)
	v_add_u32_e32 v5, v6, v5
	ds_write_b32 v4, v5 offset:32
	v_readlane_b32 s1, v255, 21
	s_waitcnt vmcnt(0) expcnt(0) lgkmcnt(0)
	s_nop 0
	v_mov_b32_e32 v1, s1
	ds_read_b32 v3, v1
	v_readlane_b32 s1, v255, 22
	s_waitcnt lgkmcnt(0)
	v_cmp_ne_u32_e32 vcc, 0, v3
	v_mov_b32_e32 v1, s1
	ds_read_b32 v2, v1
	s_cbranch_vccnz .LBB0_1433
	s_mov_b32 s4, 1
	s_branch .LBB0_1421

; __device__ __forceinline__ unsigned xb_add(unsigned* p, unsigned v) { return __hip_atomic_fetch_add(p, v, __ATOMIC_RELAXED, __HIP_MEMORY_SCOPE_AGENT); }
; __device__ __forceinline__ void xcd_barrier(const XcdBarrier& b) {
;     ...
;         const unsigned old = xb_add(&bar[XB_XSUB(b.x)], 1u);
;         const unsigned gen = old / nloc;
;         if (old + 1u == (gen + 1u) * nloc) {
;             __builtin_amdgcn_fence(__ATOMIC_RELEASE, "agent");
;             asm volatile("s_waitcnt vmcnt(0)" ::: "memory");
;             const unsigned og = xb_add(&bar[XB_TOP], 1u);
.LBB0_1449:
	s_andn2_saveexec_b64 s[6:7], s[6:7]
	s_cbranch_execz .LBB0_1469
	v_readlane_b32 s8, v253, 40
	v_readlane_b32 s9, v253, 41
	v_mov_b32_e32 v1, 0x26a38
	ds_read_b32 v1, v1
	s_nop 2
	global_atomic_add v99, v195, s[8:9] offset:576
	s_waitcnt lgkmcnt(0)
	v_cmp_ne_u32_e32 vcc, 0, v1
	s_cbranch_vccnz .Lxcd_local_3
	s_mov_b64 s[6:7], exec
	buffer_wbl2 sc1
	s_waitcnt lgkmcnt(0)
	s_waitcnt vmcnt(0)
	v_mbcnt_lo_u32_b32 v1, s6, 0
	v_mbcnt_hi_u32_b32 v1, s7, v1
	v_cmp_eq_u32_e32 vcc, 0, v1
	s_and_saveexec_b64 s[8:9], vcc
	s_cbranch_execz .LBB0_1452
	s_bcnt1_i32_b64 s4, s[6:7]
	v_readlane_b32 s6, v253, 38
	v_mov_b32_e32 v3, s4
	v_readlane_b32 s7, v253, 39
	s_nop 4
	global_atomic_add v3, v99, v3, s[6:7] sc0

; #define PHASE() size_t z_ = 0; asm volatile("" : "+s"(z_)); unsigned char* ws = args.ws + z_; float* H = args.out + z_; (void)H; (void)ws;
; #define CONVERT_P(LY, I0, ISTEP) do { const f32x4* src = (const f32x4*)(args.in[1 + z_] + (size_t)(LY) * M * DPLE); u32x2* dst = (u32x2*)PB; \
;             for (size_t i = (size_t)(I0) * 512 + tid; i < (size_t)M * DPLE / 4; i += (size_t)(ISTEP) * 512) { const f32x4 v = __builtin_nontemporal_load(src + i); u32x2 w; w.x = pk2(v[0], v[1]); w.y = pk2(v[2], v[3]); dst[i] = w; } } while (0)
; #define RELANE() int tid = threadIdx.x; asm volatile("" : "+v"(tid)); const int lane = tid & 63; (void)lane;
; __global__ void __launch_bounds__(512, 2) hybrid_fwd(Args args) {
;     ...
;         if (layer == 0 && tailfill && cgem >= G / 2) { RELANE(); PHASE(); CONVERT_WEIGHTS(1, cgem - G / 2, G / 2, 0, W_NA); CONVERT_P(1, cgem - G / 2, G / 2); }
.LBB0_1490:
	v_readlane_b32 s2, v252, 15
	v_readlane_b32 s6, v255, 28
	v_readlane_b32 s3, v252, 16
	v_readlane_b32 s7, v255, 29
	s_and_b64 s[2:3], s[6:7], s[2:3]
	v_readlane_b32 s6, v255, 50
	s_xor_b64 s[2:3], s[2:3], -1
	v_readlane_b32 s7, v255, 51
	s_or_b64 s[2:3], s[2:3], s[6:7]
	s_andn2_b64 vcc, exec, s[2:3]
	s_cbranch_vccz .LBB0_1694
	v_mov_b32_e32 v1, 0x26a44
	ds_read_b32 v1, v1
	v_readlane_b32 s6, v253, 40
	v_readlane_b32 s7, v253, 41
	v_mov_b32_e32 v2, 0
	s_mov_b32 s8, 0
	s_waitcnt lgkmcnt(0)
	v_readfirstlane_b32 s2, v1
	s_nop 0
.Lp6done_spin:
	global_load_dword v1, v2, s[6:7] offset:576 sc1
	s_waitcnt vmcnt(0)
	v_readfirstlane_b32 s3, v1
	s_cmp_ge_u32 s3, s2
	s_cbranch_scc1 .Lp6done_ok
	s_sleep 2
	s_add_i32 s8, s8, 1
	s_cmp_lt_u32 s8, 0x100000
	s_cbranch_scc1 .Lp6done_spin
.Lp6done_ok:
	v_mov_b32_e32 v38, v194
	s_mov_b64 s[2:3], 0
	s_lshl_b64 s[6:7], s[2:3], 3
	v_readlane_b32 s8, v252, 0
	v_readlane_b32 s9, v252, 1
	s_add_u32 s6, s8, s6
	s_addc_u32 s7, s9, s7
	v_readlane_b32 s8, v255, 32
	s_sub_i32 s14, s27, s8
	s_cmpk_gt_i32 s14, 0x2f3
	v_readlane_b32 s9, v255, 33
	s_cbranch_scc1 .LBB0_1690
	s_load_dwordx4 s[8:11], s[6:7], 0x60
	v_readlane_b32 s16, v252, 7
	v_readlane_b32 s17, v252, 8
	s_add_u32 s16, s16, s2
	s_addc_u32 s17, s17, s3
	s_waitcnt lgkmcnt(0)
	s_add_u32 s13, s8, 0x800
	v_lshlrev_b32_e32 v1, 2, v38
	s_load_dwordx8 s[52:59], s[6:7], 0x38
	s_load_dwordx2 s[30:31], s[6:7], 0x58
	s_addc_u32 s15, s9, 0
	s_load_dwordx2 s[8:9], s[6:7], 0xa8
	s_load_dwordx2 s[34:35], s[6:7], 0x70
	s_load_dwordx2 s[36:37], s[6:7], 0x10
	s_load_dwordx8 s[60:67], s[6:7], 0x18
	v_and_b32_e32 v1, 0xfc, v1
	v_lshlrev_b32_e32 v98, 2, v1
	s_waitcnt lgkmcnt(0)
	v_lshl_add_u64 v[2:3], s[8:9], 0, v[98:99]
	s_mov_b64 s[8:9], 0x100000
	v_lshl_add_u64 v[40:41], v[2:3], 0, s[8:9]
	v_lshlrev_b32_e32 v2, 3, v38
	v_and_b32_e32 v2, 56, v2
	v_mul_u32_u24_e32 v39, 0x410, v2
	v_lshlrev_b32_e32 v2, 1, v2
	v_mov_b32_e32 v3, v99
	v_lshl_add_u64 v[42:43], s[16:17], 0, v[2:3]
	v_add_u32_e32 v2, 0x200, v38
	v_ashrrev_i32_e32 v72, 3, v2
	v_add_u32_e32 v2, 0x400, v38
	s_mov_b64 s[8:9], 0x2a00000
	v_ashrrev_i32_e32 v73, 3, v2
	v_add_u32_e32 v2, 0x600, v38
	v_lshl_add_u64 v[44:45], v[42:43], 0, s[8:9]
	v_ashrrev_i32_e32 v74, 3, v2
	v_lshl_add_u64 v[2:3], s[34:35], 0, v[98:99]
	s_mov_b64 s[8:9], 0x400000
	v_lshl_add_u64 v[46:47], v[2:3], 0, s[8:9]
	s_mov_b64 s[8:9], 0x2500000
	v_lshl_add_u64 v[48:49], v[42:43], 0, s[8:9]
	v_lshl_add_u64 v[2:3], s[30:31], 0, v[98:99]
	s_mov_b64 s[8:9], 0x80000
	v_lshl_add_u64 v[50:51], v[2:3], 0, s[8:9]
	s_mov_b64 s[8:9], 0x2980000
	v_lshl_add_u64 v[52:53], v[42:43], 0, s[8:9]
	v_lshl_add_u64 v[2:3], s[56:57], 0, v[98:99]
	s_mov_b64 s[8:9], 0xc0000
	v_lshl_add_u64 v[54:55], v[2:3], 0, s[8:9]
	s_mov_b64 s[8:9], 0x2900000
	v_lshl_add_u64 v[56:57], v[42:43], 0, s[8:9]
	v_lshl_add_u64 v[2:3], s[52:53], 0, v[98:99]
	s_mov_b64 s[8:9], 0x7c0000
	v_lshl_add_u64 v[58:59], v[2:3], 0, s[8:9]
	s_mov_b64 s[8:9], 0x2100000
	v_lshl_add_u64 v[60:61], v[42:43], 0, s[8:9]
	v_lshl_add_u64 v[2:3], s[64:65], 0, v[98:99]
	s_mov_b64 s[8:9], 0xb00000
	v_lshl_add_u64 v[62:63], v[2:3], 0, s[8:9]
	v_lshl_add_u64 v[2:3], s[62:63], 0, v[98:99]
	v_lshl_add_u64 v[66:67], v[2:3], 0, s[8:9]
	v_lshl_add_u64 v[2:3], s[60:61], 0, v[98:99]
	s_lshl_b32 s60, s87, 2
	v_lshl_add_u64 v[64:65], v[42:43], 0, s[8:9]
	v_lshl_add_u64 v[68:69], v[2:3], 0, s[8:9]
	s_add_u32 s8, s58, s60
	s_addc_u32 s9, s59, 0
	s_add_u32 s40, s54, s60
	s_addc_u32 s41, s55, 0
	s_add_u32 s4, s66, s60
	s_addc_u32 s16, s67, 0
	s_add_u32 s58, s4, 0x1000
	s_addc_u32 s59, s16, 0
	s_add_u32 s4, s36, s60
	s_addc_u32 s16, s37, 0
	v_ashrrev_i32_e32 v71, 3, v38
	s_movk_i32 s1, 0x80
	s_add_u32 s50, s4, 0x1000
	v_cmp_lt_u32_sdwa s[42:43], v71, s1 src0_sel:BYTE_0 src1_sel:DWORD
	v_cmp_lt_u32_sdwa s[44:45], v72, s1 src0_sel:BYTE_0 src1_sel:DWORD
	v_cmp_lt_u32_sdwa s[46:47], v73, s1 src0_sel:BYTE_0 src1_sel:DWORD
	v_cmp_lt_u32_sdwa s[48:49], v74, s1 src0_sel:BYTE_0 src1_sel:DWORD
	s_addc_u32 s51, s16, 0
	s_lshl_b32 s4, s27, 8
	v_readlane_b32 s1, v255, 11
	s_sub_i32 s61, s1, s4
	v_readlane_b32 s1, v255, 12
	s_add_i32 s62, s1, s27
	v_readlane_b32 s1, v254, 57
	s_add_i32 s63, s1, s4
	v_readlane_b32 s1, v255, 13
	s_add_i32 s64, s1, s27
	v_readlane_b32 s1, v255, 14
	s_add_i32 s65, s1, s4
	v_readlane_b32 s1, v255, 15
	s_add_i32 s66, s1, s4
	v_readlane_b32 s1, v255, 16
	s_add_i32 s67, s1, s27
	v_readlane_b32 s1, v254, 56
	s_add_i32 s68, s1, s27
	s_lshl_b32 s16, s27, 9
	v_readlane_b32 s1, v254, 60
	s_add_i32 s69, s1, s16
	v_readlane_b32 s1, v255, 18
	s_add_i32 s70, s1, s4
	v_readlane_b32 s1, v254, 58
	v_and_b32_e32 v79, 0x7f, v71
	v_and_b32_e32 v80, 0x7f, v72
	v_and_b32_e32 v81, 0x7f, v73
	v_and_b32_e32 v82, 0x7f, v74
	v_lshlrev_b32_e32 v101, 1, v74
	v_lshlrev_b32_e32 v104, 1, v73
	v_lshlrev_b32_e32 v107, 1, v72
	v_lshlrev_b32_e32 v110, 1, v71
	s_add_i32 s71, s1, s27
	v_readlane_b32 s1, v254, 59
	v_add_u32_sdwa v75, v71, s5 dst_sel:DWORD dst_unused:UNUSED_PAD src0_sel:BYTE_0 src1_sel:DWORD
	v_add_u32_sdwa v76, v72, s5 dst_sel:DWORD dst_unused:UNUSED_PAD src0_sel:BYTE_0 src1_sel:DWORD
	v_add_u32_sdwa v77, v73, s5 dst_sel:DWORD dst_unused:UNUSED_PAD src0_sel:BYTE_0 src1_sel:DWORD
	v_add_u32_sdwa v78, v74, s5 dst_sel:DWORD dst_unused:UNUSED_PAD src0_sel:BYTE_0 src1_sel:DWORD
	v_or_b32_e32 v83, 0x80, v79
	v_or_b32_e32 v84, 0x80, v80
	v_or_b32_e32 v85, 0x80, v81
	v_or_b32_e32 v86, 0x80, v82
	v_add_u32_e32 v87, 0xfffd1c00, v74
	v_add_u32_e32 v88, 0xfffd1c00, v73
	v_add_u32_e32 v89, 0xfffd1c00, v72
	v_add_u32_e32 v90, 0xfffd1c00, v71
	v_add_u32_e32 v91, 0xfffd5c00, v74
	v_add_u32_e32 v92, 0xfffd5c00, v73
	v_add_u32_e32 v93, 0xfffd5c00, v72
	v_add_u32_e32 v94, 0xfffd5c00, v71
	v_add_u32_e32 v95, 0xfffd7000, v71
	v_add_u32_e32 v96, 0xfffd7000, v72
	v_add_u32_e32 v97, 0xfffd7000, v73
	v_add_u32_e32 v98, 0xfffd7000, v74
	v_add_u32_e32 v100, 0xfffdf000, v74
	v_add_u32_e32 v102, 0xfffbd680, v101
	v_add_u32_e32 v103, 0xfffdf000, v73
	v_add_u32_e32 v105, 0xfffbd680, v104
	v_add_u32_e32 v106, 0xfffdf000, v72
	v_add_u32_e32 v108, 0xfffbd680, v107
	v_add_u32_e32 v109, 0xfffdf000, v71
	v_add_u32_e32 v111, 0xfffbd680, v110
	v_add_u32_e32 v112, 0xfffea000, v74
	v_add_u32_e32 v113, 0xfffea000, v73
	v_add_u32_e32 v114, 0xfffea000, v72
	v_add_u32_e32 v115, 0xfffea000, v71
	s_add_i32 s72, s1, s27
	v_add_u32_e32 v116, 0xfffea000, v110
	v_add_u32_e32 v117, 0xfffea000, v107
	v_add_u32_e32 v118, 0xfffea000, v104
	v_add_u32_e32 v119, 0xfffea000, v101
	s_mov_b32 s73, 0
	s_mov_b32 s74, s14
	s_mov_b32 s75, 0
	s_branch .LBB0_1495
